# rebalanced P2a pool items (KU=12) with 64 B of nop padding after P2a so later loops keep their 128 B alignment
# speedup vs baseline: 1.0019x; 1.0012x over previous
.Lpool_done:
	s_nop 0
	s_nop 0
	s_nop 0
	s_nop 0
	s_nop 0
	s_nop 0
	s_nop 0
	s_nop 0
	s_nop 0
	s_nop 0
	s_nop 0
	s_nop 0
	s_nop 0
	s_nop 0
	s_nop 0
	s_nop 0
	s_waitcnt vmcnt(0)
	s_waitcnt vmcnt(0) lgkmcnt(0)
	s_barrier
	s_mov_b64 s[0:1], exec
	v_readlane_b32 s2, v253, 51
	v_readlane_b32 s3, v253, 52
	s_and_b64 s[2:3], s[0:1], s[2:3]
	s_mov_b64 exec, s[2:3]
	s_cbranch_execz .LBB0_702
	s_add_i32 s2, 0, 0x20800
	v_mov_b32_e32 v0, s2
	s_waitcnt vmcnt(0) expcnt(0) lgkmcnt(0)
	ds_read_b32 v2, v0
	s_add_i32 s2, 0, 0x20804
	v_mov_b32_e32 v0, s2
	ds_read_b32 v0, v0
	s_waitcnt lgkmcnt(1)
	v_cmp_ne_u32_e32 vcc, 0, v2
	s_cbranch_vccnz .LBB0_666
	v_readlane_b32 s2, v253, 1
	s_mul_i32 s18, s93, s2
	s_add_u32 s2, s90, 0x1000
	s_addc_u32 s3, s91, 0
	s_add_u32 s4, s90, 0x1100
	s_addc_u32 s5, s91, 0
	s_add_u32 s6, s90, 0x1200
	s_addc_u32 s7, s91, 0
	s_add_u32 s8, s90, 0x1300
	s_mul_i32 s18, s18, s92
	s_addc_u32 s9, s91, 0
	s_mov_b32 s19, 1
	v_mov_b32_e32 v16, 0
	s_branch .LBB0_654
